# stack: mixer A extended table + K/V prefetch, ATTB tables built once per phase, CMP query prefetch, no vmcnt drain before GEMM units
# speedup vs baseline: 1.0070x; 1.0070x over previous
; #define MFMA16(a, b, c) __builtin_amdgcn_mfma_f32_16x16x32_bf16((a), (b), (c), 0, 0, 0)
; template <int MODE>
; __device__ __forceinline__ void attn_wave(LAS unsigned char* lds, const bf16_t* qkv, bf16_t* Yout, const float* sinks, int wi) {
;     ...
;             bool live = (k0 <= q0 + QSTEP * qt + 15);
;             if (MODE == MODE_A) live = live && (q0 + QSTEP * qt - (k0 + 31) < 128);
;             if (MODE == MODE_C) { const bool dq = __all(carry[qt] < -150.1f); live = live && !dq; }
;             if (!live) continue;
;             f32x4 s[2];
; #pragma unroll
;             for (int nt = 0; nt < 2; ++nt) { f32x4 z = (f32x4){0.f, 0.f, 0.f, 0.f}; z = MFMA16(kf[nt][0], qf[qt][0], z); s[nt] = MFMA16(kf[nt][1], qf[qt][1], z); }
;             const int dbase = q0 + QSTEP * qt + c - k0 - 4 * g;
;             if (MODE == MODE_A) {
;                 float mx = -1e30f;
; #pragma unroll
;                 for (int nt = 0; nt < 2; ++nt)
; #pragma unroll
;                     for (int j = 0; j < 4; ++j) { const int dist = dbase - (16 * nt + j); const bool valid = (unsigned)dist < 128u;
;                         const float bias2 = lutp[qt * HSTEP * 128 + (dist & 127)];
;                         const float lg = valid ? (s[nt][j] * C1 + bias2) : -1e30f; s[nt][j] = lg; mx = fmaxf(mx, lg); }
;                 mx = fmaxf(mx, __shfl_xor(mx, 16)); mx = fmaxf(mx, __shfl_xor(mx, 32));
;                 const float mnew = fmaxf(mrun[qt], mx); const float alpha = __builtin_amdgcn_exp2f(mrun[qt] - mnew); mrun[qt] = mnew;
;                 float ps = 0.f;
; #pragma unroll
;                 for (int nt = 0; nt < 2; ++nt)
; #pragma unroll
;                     for (int j = 0; j < 4; ++j) { const float p = __builtin_amdgcn_exp2f(s[nt][j] - mnew); s[nt][j] = p; ps += p; }
;                 lrun[qt] = lrun[qt] * alpha + ps;
; #pragma unroll
;                 for (int dt = 0; dt < 4; ++dt) o[qt][dt] = o[qt][dt] * alpha;
.LBB0_264:
	v_mfma_f32_16x16x32_bf16 v[136:139], v[120:123], v[72:75], 0
	v_mfma_f32_16x16x32_bf16 v[140:143], v[124:127], v[76:79], v[136:139]
	v_mfma_f32_16x16x32_bf16 v[136:139], v[132:135], v[72:75], 0
	v_mfma_f32_16x16x32_bf16 v[136:139], v[128:131], v[76:79], v[136:139]
	v_lshlrev_b32_e32 v236, 2, v170
	v_lshl_add_u32 v236, s19, 1, v236
	v_add_u32_e32 v236, 0x140b0, v236
	ds_read_b32 v228, v236 offset:76
	ds_read_b32 v229, v236 offset:72
	ds_read_b32 v230, v236 offset:68
	ds_read_b32 v231, v236 offset:64
	ds_read_b32 v232, v236 offset:12
	ds_read_b32 v233, v236 offset:8
	ds_read_b32 v234, v236 offset:4
	ds_read_b32 v235, v236 offset:0
	v_mov_b32_e32 v237, 0x3e38aa3b
	s_waitcnt lgkmcnt(0)
	v_fma_f32 v173, v140, v237, v228
	v_fma_f32 v172, v141, v237, v229
	v_fma_f32 v141, v142, v237, v230
	v_fma_f32 v140, v143, v237, v231
	v_fma_f32 v143, v136, v237, v232
	v_fma_f32 v142, v137, v237, v233
	v_fma_f32 v137, v138, v237, v234
	v_fma_f32 v136, v139, v237, v235
	v_max3_f32 v138, v173, s86, v172
	v_max3_f32 v138, v138, v141, v140
	v_cmp_lt_i32_e32 vcc, v223, v218
	v_max3_f32 v138, v138, v143, v142
	v_max3_f32 v138, v138, v137, v136
	v_cndmask_b32_e32 v139, v217, v223, vcc
	v_lshlrev_b32_e32 v139, 2, v139
	ds_bpermute_b32 v139, v139, v138
	v_cmp_lt_i32_e32 vcc, v224, v218
	s_waitcnt lgkmcnt(0)
	v_max_f32_e32 v139, v139, v139
	v_max_f32_e32 v138, v138, v139
	v_cndmask_b32_e32 v139, v217, v224, vcc
	v_lshlrev_b32_e32 v139, 2, v139
	ds_bpermute_b32 v139, v139, v138
	s_waitcnt lgkmcnt(0)
	v_max3_f32 v174, v163, v138, v139
	v_sub_f32_e32 v139, v173, v174
	v_exp_f32_e32 v139, v139
	v_sub_f32_e32 v172, v172, v174
	v_exp_f32_e32 v172, v172
	v_sub_f32_e32 v141, v141, v174
	v_exp_f32_e32 v141, v141
	v_sub_f32_e32 v140, v140, v174
	v_exp_f32_e32 v140, v140
	v_sub_f32_e32 v143, v143, v174
	v_sub_f32_e32 v138, v163, v174
	v_add_f32_e32 v163, 0, v139
	v_exp_f32_e32 v143, v143
	v_sub_f32_e32 v142, v142, v174
	v_add_f32_e32 v163, v172, v163
	v_exp_f32_e32 v142, v142
	v_sub_f32_e32 v137, v137, v174
	v_add_f32_e32 v163, v141, v163
	v_exp_f32_e32 v173, v137
	v_add_f32_e32 v163, v140, v163
	v_add_f32_e32 v163, v143, v163
	v_add_f32_e32 v163, v142, v163
	v_sub_f32_e32 v136, v136, v174
	v_add_f32_e32 v137, v173, v163
	v_exp_f32_e32 v163, v136
	v_exp_f32_e32 v136, v138
	v_cvt_pk_bf16_f32 v138, v143, v142
	v_add_f32_e32 v175, v163, v137
	v_fmac_f32_e32 v175, v164, v136
	v_pk_mul_f32 v[58:59], v[58:59], v[136:137] op_sel_hi:[1,0]
	v_pk_mul_f32 v[56:57], v[56:57], v[136:137] op_sel_hi:[1,0]
	v_pk_mul_f32 v[62:63], v[62:63], v[136:137] op_sel_hi:[1,0]
	v_pk_mul_f32 v[60:61], v[60:61], v[136:137] op_sel_hi:[1,0]
	v_pk_mul_f32 v[66:67], v[66:67], v[136:137] op_sel_hi:[1,0]
	v_pk_mul_f32 v[64:65], v[64:65], v[136:137] op_sel_hi:[1,0]
	v_pk_mul_f32 v[70:71], v[70:71], v[136:137] op_sel_hi:[1,0]
	v_pk_mul_f32 v[68:69], v[68:69], v[136:137] op_sel_hi:[1,0]
	v_cvt_pk_bf16_f32 v136, v139, v172
	v_cvt_pk_bf16_f32 v137, v141, v140
	v_cvt_pk_bf16_f32 v139, v173, v163
	v_mov_b32_e32 v164, v175
	v_mov_b32_e32 v163, v174
	v_mfma_f32_16x16x32_bf16 v[56:59], v[116:119], v[136:139], v[56:59]
	v_mfma_f32_16x16x32_bf16 v[60:63], v[112:115], v[136:139], v[60:63]
	v_mfma_f32_16x16x32_bf16 v[64:67], v[108:111], v[136:139], v[64:67]
	v_mfma_f32_16x16x32_bf16 v[68:71], v[104:107], v[136:139], v[68:71]
	s_and_b64 vcc, exec, s[4:5]
	s_cbranch_vccnz .LBB0_262
.LBB0_281:
	v_mfma_f32_16x16x32_bf16 v[136:139], v[120:123], v[80:83], 0
	v_mfma_f32_16x16x32_bf16 v[140:143], v[124:127], v[84:87], v[136:139]
	v_mfma_f32_16x16x32_bf16 v[136:139], v[132:135], v[80:83], 0
	v_mfma_f32_16x16x32_bf16 v[136:139], v[128:131], v[84:87], v[136:139]
	v_lshlrev_b32_e32 v236, 2, v170
	v_lshl_add_u32 v236, s19, 1, v236
	v_add_u32_e32 v236, 0x140b0, v236
	ds_read_b32 v228, v236 offset:1100
	ds_read_b32 v229, v236 offset:1096
	ds_read_b32 v230, v236 offset:1092
	ds_read_b32 v231, v236 offset:1088
	ds_read_b32 v232, v236 offset:1036
	ds_read_b32 v233, v236 offset:1032
	ds_read_b32 v234, v236 offset:1028
	ds_read_b32 v235, v236 offset:1024
	v_mov_b32_e32 v237, 0x3e38aa3b
	s_waitcnt lgkmcnt(0)
	v_fma_f32 v173, v140, v237, v228
	v_fma_f32 v172, v141, v237, v229
	v_fma_f32 v141, v142, v237, v230
	v_fma_f32 v140, v143, v237, v231
	v_fma_f32 v143, v136, v237, v232
	v_fma_f32 v142, v137, v237, v233
	v_fma_f32 v137, v138, v237, v234
	v_fma_f32 v136, v139, v237, v235
	v_max3_f32 v138, v173, s86, v172
	v_max3_f32 v138, v138, v141, v140
	v_cmp_lt_i32_e32 vcc, v223, v218
	v_max3_f32 v138, v138, v143, v142
	v_max3_f32 v138, v138, v137, v136
	v_cndmask_b32_e32 v139, v217, v223, vcc
	v_lshlrev_b32_e32 v139, 2, v139
	ds_bpermute_b32 v139, v139, v138
	v_cmp_lt_i32_e32 vcc, v224, v218
	s_waitcnt lgkmcnt(0)
	v_max_f32_e32 v139, v139, v139
	v_max_f32_e32 v138, v138, v139
	v_cndmask_b32_e32 v139, v217, v224, vcc
	v_lshlrev_b32_e32 v139, 2, v139
	ds_bpermute_b32 v139, v139, v138
	s_waitcnt lgkmcnt(0)
	v_max3_f32 v174, v162, v138, v139
	v_sub_f32_e32 v139, v173, v174
	v_exp_f32_e32 v139, v139
	v_sub_f32_e32 v172, v172, v174
	v_exp_f32_e32 v172, v172
	v_sub_f32_e32 v141, v141, v174
	v_exp_f32_e32 v141, v141
	v_sub_f32_e32 v140, v140, v174
	v_exp_f32_e32 v140, v140
	v_sub_f32_e32 v143, v143, v174
	v_sub_f32_e32 v138, v162, v174
	v_add_f32_e32 v162, 0, v139
	v_exp_f32_e32 v143, v143
	v_sub_f32_e32 v142, v142, v174
	v_add_f32_e32 v162, v172, v162
	v_exp_f32_e32 v142, v142
	v_sub_f32_e32 v137, v137, v174
	v_add_f32_e32 v162, v141, v162
	v_exp_f32_e32 v173, v137
	v_add_f32_e32 v162, v140, v162
	v_add_f32_e32 v162, v143, v162
	v_add_f32_e32 v162, v142, v162
	v_sub_f32_e32 v136, v136, v174
	v_add_f32_e32 v137, v173, v162
	v_exp_f32_e32 v162, v136
	v_exp_f32_e32 v136, v138
	v_cvt_pk_bf16_f32 v138, v143, v142
	v_add_f32_e32 v175, v162, v137
	v_fmac_f32_e32 v175, v161, v136
	v_pk_mul_f32 v[42:43], v[42:43], v[136:137] op_sel_hi:[1,0]
	v_pk_mul_f32 v[40:41], v[40:41], v[136:137] op_sel_hi:[1,0]
	v_pk_mul_f32 v[46:47], v[46:47], v[136:137] op_sel_hi:[1,0]
	v_pk_mul_f32 v[44:45], v[44:45], v[136:137] op_sel_hi:[1,0]
	v_pk_mul_f32 v[50:51], v[50:51], v[136:137] op_sel_hi:[1,0]
	v_pk_mul_f32 v[48:49], v[48:49], v[136:137] op_sel_hi:[1,0]
	v_pk_mul_f32 v[54:55], v[54:55], v[136:137] op_sel_hi:[1,0]
	v_pk_mul_f32 v[52:53], v[52:53], v[136:137] op_sel_hi:[1,0]
	v_cvt_pk_bf16_f32 v136, v139, v172
	v_cvt_pk_bf16_f32 v137, v141, v140
	v_cvt_pk_bf16_f32 v139, v173, v162
	v_mov_b32_e32 v161, v175
	v_mov_b32_e32 v162, v174
	v_mfma_f32_16x16x32_bf16 v[40:43], v[116:119], v[136:139], v[40:43]
	v_mfma_f32_16x16x32_bf16 v[44:47], v[112:115], v[136:139], v[44:47]
	v_mfma_f32_16x16x32_bf16 v[48:51], v[108:111], v[136:139], v[48:51]
	v_mfma_f32_16x16x32_bf16 v[52:55], v[104:107], v[136:139], v[52:55]
	s_and_b64 vcc, exec, s[4:5]
	s_cbranch_vccnz .LBB0_263
; #define MFMA16(a, b, c) __builtin_amdgcn_mfma_f32_16x16x32_bf16((a), (b), (c), 0, 0, 0)
; template <int MODE>
; __device__ __forceinline__ void attn_wave(LAS unsigned char* lds, const bf16_t* qkv, bf16_t* Yout, const float* sinks, int wi) {
;     ...
;             bool live = (k0 <= q0 + QSTEP * qt + 15);
;             if (MODE == MODE_A) live = live && (q0 + QSTEP * qt - (k0 + 31) < 128);
;             if (MODE == MODE_C) { const bool dq = __all(carry[qt] < -150.1f); live = live && !dq; }
;             if (!live) continue;
;             f32x4 s[2];
; #pragma unroll
;             for (int nt = 0; nt < 2; ++nt) { f32x4 z = (f32x4){0.f, 0.f, 0.f, 0.f}; z = MFMA16(kf[nt][0], qf[qt][0], z); s[nt] = MFMA16(kf[nt][1], qf[qt][1], z); }
;             const int dbase = q0 + QSTEP * qt + c - k0 - 4 * g;
;             if (MODE == MODE_A) {
;                 float mx = -1e30f;
; #pragma unroll
;                 for (int nt = 0; nt < 2; ++nt)
; #pragma unroll
;                     for (int j = 0; j < 4; ++j) { const int dist = dbase - (16 * nt + j); const bool valid = (unsigned)dist < 128u;
;                         const float bias2 = lutp[qt * HSTEP * 128 + (dist & 127)];
;                         const float lg = valid ? (s[nt][j] * C1 + bias2) : -1e30f; s[nt][j] = lg; mx = fmaxf(mx, lg); }
;                 mx = fmaxf(mx, __shfl_xor(mx, 16)); mx = fmaxf(mx, __shfl_xor(mx, 32));
;                 const float mnew = fmaxf(mrun[qt], mx); const float alpha = __builtin_amdgcn_exp2f(mrun[qt] - mnew); mrun[qt] = mnew;
;                 float ps = 0.f;
; #pragma unroll
;                 for (int nt = 0; nt < 2; ++nt)
; #pragma unroll
;                     for (int j = 0; j < 4; ++j) { const float p = __builtin_amdgcn_exp2f(s[nt][j] - mnew); s[nt][j] = p; ps += p; }
;                 lrun[qt] = lrun[qt] * alpha + ps;
; #pragma unroll
;                 for (int dt = 0; dt < 4; ++dt) o[qt][dt] = o[qt][dt] * alpha;
.LBB0_298:
	v_mfma_f32_16x16x32_bf16 v[136:139], v[120:123], v[88:91], 0
	v_mfma_f32_16x16x32_bf16 v[140:143], v[124:127], v[92:95], v[136:139]
	v_mfma_f32_16x16x32_bf16 v[136:139], v[132:135], v[88:91], 0
	v_mfma_f32_16x16x32_bf16 v[136:139], v[128:131], v[92:95], v[136:139]
	v_lshlrev_b32_e32 v236, 2, v170
	v_lshl_add_u32 v236, s19, 1, v236
	v_add_u32_e32 v236, 0x140b0, v236
	ds_read_b32 v228, v236 offset:2124
	ds_read_b32 v229, v236 offset:2120
	ds_read_b32 v230, v236 offset:2116
	ds_read_b32 v231, v236 offset:2112
	ds_read_b32 v232, v236 offset:2060
	ds_read_b32 v233, v236 offset:2056
	ds_read_b32 v234, v236 offset:2052
	ds_read_b32 v235, v236 offset:2048
	v_mov_b32_e32 v237, 0x3e38aa3b
	s_waitcnt lgkmcnt(0)
	v_fma_f32 v173, v140, v237, v228
	v_fma_f32 v172, v141, v237, v229
	v_fma_f32 v141, v142, v237, v230
	v_fma_f32 v140, v143, v237, v231
	v_fma_f32 v143, v136, v237, v232
	v_fma_f32 v142, v137, v237, v233
	v_fma_f32 v137, v138, v237, v234
	v_fma_f32 v136, v139, v237, v235
	v_max3_f32 v138, v173, s86, v172
	v_max3_f32 v138, v138, v141, v140
	v_cmp_lt_i32_e32 vcc, v223, v218
	v_max3_f32 v138, v138, v143, v142
	v_max3_f32 v138, v138, v137, v136
	v_cndmask_b32_e32 v139, v217, v223, vcc
	v_lshlrev_b32_e32 v139, 2, v139
	ds_bpermute_b32 v139, v139, v138
	v_cmp_lt_i32_e32 vcc, v224, v218
	s_waitcnt lgkmcnt(0)
	v_max_f32_e32 v139, v139, v139
	v_max_f32_e32 v138, v138, v139
	v_cndmask_b32_e32 v139, v217, v224, vcc
	v_lshlrev_b32_e32 v139, 2, v139
	ds_bpermute_b32 v139, v139, v138
	s_waitcnt lgkmcnt(0)
	v_max3_f32 v174, v159, v138, v139
	v_sub_f32_e32 v139, v173, v174
	v_exp_f32_e32 v139, v139
	v_sub_f32_e32 v172, v172, v174
	v_exp_f32_e32 v172, v172
	v_sub_f32_e32 v141, v141, v174
	v_exp_f32_e32 v141, v141
	v_sub_f32_e32 v140, v140, v174
	v_exp_f32_e32 v140, v140
	v_sub_f32_e32 v143, v143, v174
	v_sub_f32_e32 v138, v159, v174
	v_add_f32_e32 v159, 0, v139
	v_exp_f32_e32 v143, v143
	v_sub_f32_e32 v142, v142, v174
	v_add_f32_e32 v159, v172, v159
	v_exp_f32_e32 v142, v142
	v_sub_f32_e32 v137, v137, v174
	v_add_f32_e32 v159, v141, v159
	v_exp_f32_e32 v173, v137
	v_add_f32_e32 v159, v140, v159
	v_add_f32_e32 v159, v143, v159
	v_add_f32_e32 v159, v142, v159
	v_sub_f32_e32 v136, v136, v174
	v_add_f32_e32 v137, v173, v159
	v_exp_f32_e32 v159, v136
	v_exp_f32_e32 v136, v138
	v_cvt_pk_bf16_f32 v138, v143, v142
	v_add_f32_e32 v175, v159, v137
	v_fmac_f32_e32 v175, v158, v136
	v_pk_mul_f32 v[26:27], v[26:27], v[136:137] op_sel_hi:[1,0]
	v_pk_mul_f32 v[24:25], v[24:25], v[136:137] op_sel_hi:[1,0]
	v_pk_mul_f32 v[30:31], v[30:31], v[136:137] op_sel_hi:[1,0]
	v_pk_mul_f32 v[28:29], v[28:29], v[136:137] op_sel_hi:[1,0]
	v_pk_mul_f32 v[34:35], v[34:35], v[136:137] op_sel_hi:[1,0]
	v_pk_mul_f32 v[32:33], v[32:33], v[136:137] op_sel_hi:[1,0]
	v_pk_mul_f32 v[38:39], v[38:39], v[136:137] op_sel_hi:[1,0]
	v_pk_mul_f32 v[36:37], v[36:37], v[136:137] op_sel_hi:[1,0]
	v_cvt_pk_bf16_f32 v136, v139, v172
	v_cvt_pk_bf16_f32 v137, v141, v140
	v_cvt_pk_bf16_f32 v139, v173, v159
	v_mov_b32_e32 v158, v175
	v_mov_b32_e32 v159, v174
	v_mfma_f32_16x16x32_bf16 v[24:27], v[116:119], v[136:139], v[24:27]
	v_mfma_f32_16x16x32_bf16 v[28:31], v[112:115], v[136:139], v[28:31]
	v_mfma_f32_16x16x32_bf16 v[32:35], v[108:111], v[136:139], v[32:35]
	v_mfma_f32_16x16x32_bf16 v[36:39], v[104:107], v[136:139], v[36:39]
	s_and_b64 vcc, exec, s[4:5]
	s_cbranch_vccnz .LBB0_259
.LBB0_315:
	v_mfma_f32_16x16x32_bf16 v[120:123], v[120:123], v[96:99], 0
	v_mfma_f32_16x16x32_bf16 v[124:127], v[124:127], v[100:103], v[120:123]
	v_mfma_f32_16x16x32_bf16 v[120:123], v[132:135], v[96:99], 0
	v_mfma_f32_16x16x32_bf16 v[120:123], v[128:131], v[100:103], v[120:123]
	v_lshlrev_b32_e32 v236, 2, v170
	v_lshl_add_u32 v236, s19, 1, v236
	v_add_u32_e32 v236, 0x140b0, v236
	ds_read_b32 v228, v236 offset:3148
	ds_read_b32 v229, v236 offset:3144
	ds_read_b32 v230, v236 offset:3140
	ds_read_b32 v231, v236 offset:3136
	ds_read_b32 v232, v236 offset:3084
	ds_read_b32 v233, v236 offset:3080
	ds_read_b32 v234, v236 offset:3076
	ds_read_b32 v235, v236 offset:3072
	v_mov_b32_e32 v237, 0x3e38aa3b
	s_waitcnt lgkmcnt(0)
	v_fma_f32 v133, v124, v237, v228
	v_fma_f32 v132, v125, v237, v229
	v_fma_f32 v125, v126, v237, v230
	v_fma_f32 v124, v127, v237, v231
	v_fma_f32 v127, v120, v237, v232
	v_fma_f32 v126, v121, v237, v233
	v_fma_f32 v121, v122, v237, v234
	v_fma_f32 v120, v123, v237, v235
	s_branch .LBB0_258
